# v58 + arrival invalidate issued before the arrival-atomic wait (overlaps its round trip)
# speedup vs baseline: 1.0070x; 1.0070x over previous
.LBB0_111:
	s_or_b64 exec, exec, s[8:9]
	buffer_inv sc1
	v_cvt_f32_u32_e32 v5, v3
	s_waitcnt vmcnt(0)
	v_readfirstlane_b32 s6, v4
	v_sub_u32_e32 v4, 0, v3
	v_rcp_iflag_f32_e32 v5, v5
	v_add_u32_e32 v6, s6, v2
	v_mul_f32_e32 v5, 0x4f7ffffe, v5
	v_cvt_u32_f32_e32 v5, v5
	v_mul_lo_u32 v2, v4, v5
	v_mul_hi_u32 v2, v5, v2
	v_add_u32_e32 v2, v5, v2
	v_mul_hi_u32 v2, v6, v2
	v_mul_lo_u32 v4, v2, v3
	v_sub_u32_e32 v4, v6, v4
	v_add_u32_e32 v5, 1, v2
	v_cmp_ge_u32_e32 vcc, v4, v3
	s_nop 1
	v_cndmask_b32_e32 v2, v2, v5, vcc
	v_sub_u32_e32 v5, v4, v3
	v_cndmask_b32_e32 v4, v4, v5, vcc
	v_add_u32_e32 v5, 1, v2
	v_cmp_ge_u32_e32 vcc, v4, v3
	v_add_u32_e32 v4, 1, v6
	s_nop 0
	v_cndmask_b32_e32 v2, v2, v5, vcc
	v_mul_lo_u32 v5, v3, v2
	v_add_u32_e32 v3, v5, v3
	v_cmp_ne_u32_e32 vcc, v4, v3
	s_and_saveexec_b64 s[6:7], vcc
	s_xor_b64 s[6:7], exec, s[6:7]
	s_cbranch_execz .LBB0_125
	s_waitcnt lgkmcnt(0)
	v_mov_b32_e32 v1, 0x2000
	global_load_dword v1, v1, s[4:5] offset:1024 sc1
	s_add_u32 s12, s4, 0x2400
	s_addc_u32 s13, s5, 0
	s_waitcnt vmcnt(0)
	v_cmp_eq_u32_e32 vcc, v1, v2
	s_and_saveexec_b64 s[8:9], vcc
	s_cbranch_execz .LBB0_124
	s_add_u32 s10, s82, 0x4200
	s_addc_u32 s11, s83, 0
	s_mov_b32 s24, 1
	s_mov_b64 s[14:15], 0
	v_mov_b32_e32 v1, 0
	s_branch .LBB0_115

.LBB0_594:
	s_or_b64 exec, exec, s[6:7]
	buffer_inv sc1
	v_cvt_f32_u32_e32 v5, v3
	s_waitcnt vmcnt(0)
	v_readfirstlane_b32 s4, v4
	v_sub_u32_e32 v4, 0, v3
	v_rcp_iflag_f32_e32 v5, v5
	v_add_u32_e32 v6, s4, v2
	v_mul_f32_e32 v5, 0x4f7ffffe, v5
	v_cvt_u32_f32_e32 v5, v5
	v_mul_lo_u32 v2, v4, v5
	v_mul_hi_u32 v2, v5, v2
	v_add_u32_e32 v2, v5, v2
	v_mul_hi_u32 v2, v6, v2
	v_mul_lo_u32 v4, v2, v3
	v_sub_u32_e32 v4, v6, v4
	v_add_u32_e32 v5, 1, v2
	v_cmp_ge_u32_e32 vcc, v4, v3
	s_nop 1
	v_cndmask_b32_e32 v2, v2, v5, vcc
	v_sub_u32_e32 v5, v4, v3
	v_cndmask_b32_e32 v4, v4, v5, vcc
	v_add_u32_e32 v5, 1, v2
	v_cmp_ge_u32_e32 vcc, v4, v3
	v_add_u32_e32 v4, 1, v6
	s_nop 0
	v_cndmask_b32_e32 v2, v2, v5, vcc
	v_mul_lo_u32 v5, v3, v2
	v_add_u32_e32 v3, v5, v3
	v_cmp_ne_u32_e32 vcc, v4, v3
	s_and_saveexec_b64 s[4:5], vcc
	s_xor_b64 s[4:5], exec, s[4:5]
	s_cbranch_execz .LBB0_608
	s_waitcnt lgkmcnt(0)
	v_mov_b32_e32 v1, 0x2000
	global_load_dword v1, v1, s[2:3] offset:1024 sc1
	s_add_u32 s10, s2, 0x2400
	s_addc_u32 s11, s3, 0
	s_waitcnt vmcnt(0)
	v_cmp_eq_u32_e32 vcc, v1, v2
	s_and_saveexec_b64 s[6:7], vcc
	s_cbranch_execz .LBB0_607
	s_add_u32 s8, s82, 0x4200
	s_addc_u32 s9, s83, 0
	s_mov_b32 s24, 1
	s_mov_b64 s[12:13], 0
	v_mov_b32_e32 v1, 0
	s_branch .LBB0_598

.LBB0_1231:
	s_or_b64 exec, exec, s[6:7]
	buffer_inv sc1
	v_cvt_f32_u32_e32 v5, v3
	s_waitcnt vmcnt(0)
	v_readfirstlane_b32 s4, v4
	v_sub_u32_e32 v4, 0, v3
	v_rcp_iflag_f32_e32 v5, v5
	v_add_u32_e32 v6, s4, v2
	v_mul_f32_e32 v5, 0x4f7ffffe, v5
	v_cvt_u32_f32_e32 v5, v5
	v_mul_lo_u32 v2, v4, v5
	v_mul_hi_u32 v2, v5, v2
	v_add_u32_e32 v2, v5, v2
	v_mul_hi_u32 v2, v6, v2
	v_mul_lo_u32 v4, v2, v3
	v_sub_u32_e32 v4, v6, v4
	v_add_u32_e32 v5, 1, v2
	v_cmp_ge_u32_e32 vcc, v4, v3
	s_nop 1
	v_cndmask_b32_e32 v2, v2, v5, vcc
	v_sub_u32_e32 v5, v4, v3
	v_cndmask_b32_e32 v4, v4, v5, vcc
	v_add_u32_e32 v5, 1, v2
	v_cmp_ge_u32_e32 vcc, v4, v3
	v_add_u32_e32 v4, 1, v6
	s_nop 0
	v_cndmask_b32_e32 v2, v2, v5, vcc
	v_mul_lo_u32 v5, v3, v2
	v_add_u32_e32 v3, v5, v3
	v_cmp_ne_u32_e32 vcc, v4, v3
	s_and_saveexec_b64 s[4:5], vcc
	s_xor_b64 s[4:5], exec, s[4:5]
	s_cbranch_execz .LBB0_1245
	s_waitcnt lgkmcnt(0)
	v_mov_b32_e32 v1, 0x2000
	global_load_dword v1, v1, s[2:3] offset:1024 sc1
	s_add_u32 s10, s2, 0x2400
	s_addc_u32 s11, s3, 0
	s_waitcnt vmcnt(0)
	v_cmp_eq_u32_e32 vcc, v1, v2
	s_and_saveexec_b64 s[6:7], vcc
	s_cbranch_execz .LBB0_1244
	s_add_u32 s8, s82, 0x4200
	s_addc_u32 s9, s83, 0
	s_mov_b32 s22, 1
	s_mov_b64 s[12:13], 0
	v_mov_b32_e32 v1, 0
	s_branch .LBB0_1235

.LBB0_1571:
	s_or_b64 exec, exec, s[8:9]
	buffer_inv sc1
	v_cvt_f32_u32_e32 v5, v3
	s_waitcnt vmcnt(0)
	v_readfirstlane_b32 s6, v4
	v_sub_u32_e32 v4, 0, v3
	v_rcp_iflag_f32_e32 v5, v5
	v_add_u32_e32 v6, s6, v2
	v_mul_f32_e32 v5, 0x4f7ffffe, v5
	v_cvt_u32_f32_e32 v5, v5
	v_mul_lo_u32 v2, v4, v5
	v_mul_hi_u32 v2, v5, v2
	v_add_u32_e32 v2, v5, v2
	v_mul_hi_u32 v2, v6, v2
	v_mul_lo_u32 v4, v2, v3
	v_sub_u32_e32 v4, v6, v4
	v_add_u32_e32 v5, 1, v2
	v_cmp_ge_u32_e32 vcc, v4, v3
	s_nop 1
	v_cndmask_b32_e32 v2, v2, v5, vcc
	v_sub_u32_e32 v5, v4, v3
	v_cndmask_b32_e32 v4, v4, v5, vcc
	v_add_u32_e32 v5, 1, v2
	v_cmp_ge_u32_e32 vcc, v4, v3
	v_add_u32_e32 v4, 1, v6
	s_nop 0
	v_cndmask_b32_e32 v2, v2, v5, vcc
	v_mul_lo_u32 v5, v3, v2
	v_add_u32_e32 v3, v5, v3
	v_cmp_ne_u32_e32 vcc, v4, v3
	s_and_saveexec_b64 s[6:7], vcc
	s_xor_b64 s[6:7], exec, s[6:7]
	s_cbranch_execz .LBB0_1585
	s_waitcnt lgkmcnt(0)
	v_mov_b32_e32 v1, 0x2000
	global_load_dword v1, v1, s[2:3] offset:1024 sc1
	s_add_u32 s12, s2, 0x2400
	s_addc_u32 s13, s3, 0
	s_waitcnt vmcnt(0)
	v_cmp_eq_u32_e32 vcc, v1, v2
	s_and_saveexec_b64 s[8:9], vcc
	s_cbranch_execz .LBB0_1584
	s_add_u32 s10, s82, 0x4200
	s_addc_u32 s11, s83, 0
	s_mov_b32 s24, 1
	s_mov_b64 s[14:15], 0
	v_mov_b32_e32 v1, 0
	s_branch .LBB0_1575

.LBB0_1855:
	s_or_b64 exec, exec, s[6:7]
	buffer_inv sc1
	v_cvt_f32_u32_e32 v5, v3
	s_waitcnt vmcnt(0)
	v_readfirstlane_b32 s4, v4
	v_sub_u32_e32 v4, 0, v3
	v_rcp_iflag_f32_e32 v5, v5
	v_add_u32_e32 v6, s4, v2
	v_mul_f32_e32 v5, 0x4f7ffffe, v5
	v_cvt_u32_f32_e32 v5, v5
	v_mul_lo_u32 v2, v4, v5
	v_mul_hi_u32 v2, v5, v2
	v_add_u32_e32 v2, v5, v2
	v_mul_hi_u32 v2, v6, v2
	v_mul_lo_u32 v4, v2, v3
	v_sub_u32_e32 v4, v6, v4
	v_add_u32_e32 v5, 1, v2
	v_cmp_ge_u32_e32 vcc, v4, v3
	s_nop 1
	v_cndmask_b32_e32 v2, v2, v5, vcc
	v_sub_u32_e32 v5, v4, v3
	v_cndmask_b32_e32 v4, v4, v5, vcc
	v_add_u32_e32 v5, 1, v2
	v_cmp_ge_u32_e32 vcc, v4, v3
	v_add_u32_e32 v4, 1, v6
	s_nop 0
	v_cndmask_b32_e32 v2, v2, v5, vcc
	v_mul_lo_u32 v5, v3, v2
	v_add_u32_e32 v3, v5, v3
	v_cmp_ne_u32_e32 vcc, v4, v3
	s_and_saveexec_b64 s[4:5], vcc
	s_xor_b64 s[4:5], exec, s[4:5]
	s_cbranch_execz .LBB0_1869
	s_waitcnt lgkmcnt(0)
	v_mov_b32_e32 v1, 0x2000
	global_load_dword v1, v1, s[2:3] offset:1024 sc1
	s_add_u32 s12, s2, 0x2400
	s_addc_u32 s13, s3, 0
	s_waitcnt vmcnt(0)
	v_cmp_eq_u32_e32 vcc, v1, v2
	s_and_saveexec_b64 s[6:7], vcc
	s_cbranch_execz .LBB0_1868
	s_add_u32 s8, s82, 0x4200
	s_addc_u32 s9, s83, 0
	s_mov_b32 s24, 1
	s_mov_b64 s[14:15], 0
	v_mov_b32_e32 v1, 0
	s_branch .LBB0_1859
